# final rmsnorm loop rewritten: gain vector loaded once, 16 row loads in flight, no per-store vmcnt(0)
# baseline (speedup 1.0000x reference)
; __device__ __forceinline__ float bf_lo(unsigned w) { return __uint_as_float(w << 16); }
; __device__ __forceinline__ float bf_hi(unsigned w) { return __uint_as_float(w & 0xffff0000u); }
; __device__ __forceinline__ void final_norm(const Frame& F) {
;     const int gw = F.vcu * NWAVES + F.wave, NGW = F.G * NWAVES;
;     const f32x4* g4 = (const f32x4*)F.in[15] + F.lane;
;     const bf16* H3 = (const bf16*)(F.ws + WS_SEC) + 5 * SEC_ELEMS;
;     constexpr int NR = 4;
;     for (int R0 = gw; R0 < MQ; R0 += NR * NGW) {
;         u32x2 w[NR][4]; bool has[NR]; int Rr[NR];
; #pragma unroll
;         for (int rr = 0; rr < NR; ++rr) { const int R = R0 + rr * NGW; has[rr] = R < MQ; Rr[rr] = has[rr] ? R : R0; const u32x2* hr = (const u32x2*)(H3 + (size_t)Rr[rr] * DM) + F.lane;
; #pragma unroll
;             for (int j = 0; j < 4; ++j) w[rr][j] = hr[64 * j]; }
; #pragma unroll
;         for (int rr = 0; rr < NR; ++rr) { f32x4 v[4]; float s = 0.f;
; #pragma unroll
;             for (int j = 0; j < 4; ++j) { v[j] = (f32x4){pg8::bf_lo(w[rr][j].x), pg8::bf_hi(w[rr][j].x), pg8::bf_lo(w[rr][j].y), pg8::bf_hi(w[rr][j].y)}; s += (v[j].x * v[j].x + v[j].y * v[j].y) + (v[j].z * v[j].z + v[j].w * v[j].w); }
.LBB0_798:
	s_cmp_lt_i32 s78, 8
	s_cselect_b64 s[0:1], -1, 0
	s_and_b64 s[0:1], s[0:1], s[2:3]
	s_andn2_b64 vcc, exec, s[0:1]
	s_cbranch_vccnz .LBB0_808
	s_lshl_b32 s0, s77, 3
	s_add_i32 s0, s0, s85
	s_cmpk_gt_i32 s0, 0x7fff
	s_cbranch_scc1 .LBB0_808
	v_mbcnt_lo_u32_b32 v2, -1, 0
	v_mbcnt_hi_u32_b32 v2, -1, v2
	v_and_b32_e32 v3, 64, v2
	v_add_u32_e32 v3, 64, v3
	v_xor_b32_e32 v6, 1, v2
	v_cmp_lt_i32_e32 vcc, v6, v3
	v_mov_b32_e32 v5, 0
	v_lshlrev_b32_e32 v4, 4, v176
	v_cndmask_b32_e32 v6, v2, v6, vcc
	v_lshlrev_b32_e32 v38, 2, v6
	v_xor_b32_e32 v6, 2, v2
	v_cmp_lt_i32_e32 vcc, v6, v3
	s_mov_b64 s[2:3], 0x17100000
	s_lshl_b32 s12, s70, 3
	v_cndmask_b32_e32 v6, v2, v6, vcc
	v_lshlrev_b32_e32 v39, 2, v6
	v_xor_b32_e32 v6, 4, v2
	v_cmp_lt_i32_e32 vcc, v6, v3
	s_waitcnt lgkmcnt(0)
	v_lshl_add_u64 v[0:1], s[26:27], 0, v[4:5]
	s_lshl_b32 s13, s70, 4
	v_cndmask_b32_e32 v6, v2, v6, vcc
	v_lshlrev_b32_e32 v40, 2, v6
	v_xor_b32_e32 v6, 8, v2
	v_cmp_lt_i32_e32 vcc, v6, v3
	s_mul_i32 s14, s70, 24
	v_mov_b32_e32 v44, 0x358637bd
	v_cndmask_b32_e32 v6, v2, v6, vcc
	v_lshlrev_b32_e32 v41, 2, v6
	v_xor_b32_e32 v6, 16, v2
	v_cmp_lt_i32_e32 vcc, v6, v3
	s_mov_b32 s15, 0xf800000
	v_mov_b32_e32 v45, 0x260
	v_cndmask_b32_e32 v6, v2, v6, vcc
	v_lshlrev_b32_e32 v42, 2, v6
	v_xor_b32_e32 v6, 32, v2
	v_cmp_lt_i32_e32 vcc, v6, v3
	v_mov_b32_e32 v3, v5
	v_lshl_add_u64 v[4:5], s[80:81], 0, v[4:5]
	v_cndmask_b32_e32 v2, v2, v6, vcc
	v_lshlrev_b32_e32 v43, 2, v2
	v_lshlrev_b32_e32 v2, 3, v176
	v_lshl_add_u64 v[2:3], s[82:83], 0, v[2:3]
	v_lshl_add_u64 v[2:3], v[2:3], 0, s[2:3]
	global_load_dwordx4 v[100:103], v[0:1], off
	global_load_dwordx4 v[104:107], v[0:1], off offset:1024
	global_load_dwordx4 v[108:111], v[0:1], off offset:2048
	global_load_dwordx4 v[112:115], v[0:1], off offset:3072
	s_mov_b32 s3, 0
	s_branch .LBB0_802
.LBB0_802:
	s_add_i32 s4, s0, s12
	s_add_i32 s5, s0, s13
	s_add_i32 s6, s0, s14
	s_cmp_lt_i32 s4, 0x8000
	s_cselect_b32 s8, s4, s0
	s_cmp_lt_i32 s5, 0x8000
	s_cselect_b32 s9, s5, s0
	s_cmp_lt_i32 s6, 0x8000
	s_cselect_b32 s10, s6, s0
	s_lshl_b32 s2, s0, 11
	v_lshl_add_u64 v[70:71], v[2:3], 0, s[2:3]
	s_lshl_b32 s2, s8, 11
	v_lshl_add_u64 v[72:73], v[2:3], 0, s[2:3]
	s_lshl_b32 s2, s9, 11
	v_lshl_add_u64 v[74:75], v[2:3], 0, s[2:3]
	s_lshl_b32 s2, s10, 11
	v_lshl_add_u64 v[76:77], v[2:3], 0, s[2:3]
	global_load_dwordx2 v[120:121], v[70:71], off
	global_load_dwordx2 v[122:123], v[70:71], off offset:512
	global_load_dwordx2 v[124:125], v[70:71], off offset:1024
	global_load_dwordx2 v[126:127], v[70:71], off offset:1536
	global_load_dwordx2 v[128:129], v[72:73], off
	global_load_dwordx2 v[130:131], v[72:73], off offset:512
	global_load_dwordx2 v[132:133], v[72:73], off offset:1024
	global_load_dwordx2 v[134:135], v[72:73], off offset:1536
	global_load_dwordx2 v[136:137], v[74:75], off
	global_load_dwordx2 v[138:139], v[74:75], off offset:512
	global_load_dwordx2 v[140:141], v[74:75], off offset:1024
	global_load_dwordx2 v[142:143], v[74:75], off offset:1536
	global_load_dwordx2 v[144:145], v[76:77], off
	global_load_dwordx2 v[146:147], v[76:77], off offset:512
	global_load_dwordx2 v[148:149], v[76:77], off offset:1024
	global_load_dwordx2 v[150:151], v[76:77], off offset:1536
	s_waitcnt vmcnt(12)
	v_lshlrev_b32_e32 v160, 16, v120
	v_and_b32_e32 v161, 0xffff0000, v120
	v_lshlrev_b32_e32 v162, 16, v121
	v_and_b32_e32 v163, 0xffff0000, v121
	v_lshlrev_b32_e32 v164, 16, v122
	v_and_b32_e32 v165, 0xffff0000, v122
	v_lshlrev_b32_e32 v166, 16, v123
	v_and_b32_e32 v167, 0xffff0000, v123
	v_lshlrev_b32_e32 v168, 16, v124
	v_and_b32_e32 v169, 0xffff0000, v124
	v_lshlrev_b32_e32 v170, 16, v125
	v_and_b32_e32 v171, 0xffff0000, v125
	v_lshlrev_b32_e32 v172, 16, v126
	v_and_b32_e32 v173, 0xffff0000, v126
	v_lshlrev_b32_e32 v174, 16, v127
	v_and_b32_e32 v175, 0xffff0000, v127
	v_mul_f32_e32 v60, v160, v160
	v_mul_f32_e32 v61, v162, v162
	v_fmac_f32_e32 v60, v161, v161
	v_fmac_f32_e32 v61, v163, v163
	v_add_f32_e32 v96, v60, v61
	v_mul_f32_e32 v60, v164, v164
	v_mul_f32_e32 v61, v166, v166
	v_fmac_f32_e32 v60, v165, v165
	v_fmac_f32_e32 v61, v167, v167
	v_add_f32_e32 v60, v60, v61
	v_add_f32_e32 v96, v96, v60
	v_mul_f32_e32 v60, v168, v168
	v_mul_f32_e32 v61, v170, v170
	v_fmac_f32_e32 v60, v169, v169
	v_fmac_f32_e32 v61, v171, v171
	v_add_f32_e32 v60, v60, v61
	v_add_f32_e32 v96, v96, v60
	v_mul_f32_e32 v60, v172, v172
	v_mul_f32_e32 v61, v174, v174
	v_fmac_f32_e32 v60, v173, v173
	v_fmac_f32_e32 v61, v175, v175
	v_add_f32_e32 v60, v60, v61
	v_add_f32_e32 v96, v96, v60
	s_waitcnt vmcnt(8)
	v_lshlrev_b32_e32 v176, 16, v128
	v_and_b32_e32 v177, 0xffff0000, v128
	v_lshlrev_b32_e32 v178, 16, v129
	v_and_b32_e32 v179, 0xffff0000, v129
	v_lshlrev_b32_e32 v180, 16, v130
	v_and_b32_e32 v181, 0xffff0000, v130
	v_lshlrev_b32_e32 v182, 16, v131
	v_and_b32_e32 v183, 0xffff0000, v131
	v_lshlrev_b32_e32 v184, 16, v132
	v_and_b32_e32 v185, 0xffff0000, v132
	v_lshlrev_b32_e32 v186, 16, v133
	v_and_b32_e32 v187, 0xffff0000, v133
	v_lshlrev_b32_e32 v188, 16, v134
	v_and_b32_e32 v189, 0xffff0000, v134
	v_lshlrev_b32_e32 v190, 16, v135
	v_and_b32_e32 v191, 0xffff0000, v135
	v_mul_f32_e32 v60, v176, v176
	v_mul_f32_e32 v61, v178, v178
	v_fmac_f32_e32 v60, v177, v177
	v_fmac_f32_e32 v61, v179, v179
	v_add_f32_e32 v97, v60, v61
	v_mul_f32_e32 v60, v180, v180
	v_mul_f32_e32 v61, v182, v182
	v_fmac_f32_e32 v60, v181, v181
	v_fmac_f32_e32 v61, v183, v183
	v_add_f32_e32 v60, v60, v61
	v_add_f32_e32 v97, v97, v60
	v_mul_f32_e32 v60, v184, v184
	v_mul_f32_e32 v61, v186, v186
	v_fmac_f32_e32 v60, v185, v185
	v_fmac_f32_e32 v61, v187, v187
	v_add_f32_e32 v60, v60, v61
	v_add_f32_e32 v97, v97, v60
	v_mul_f32_e32 v60, v188, v188
	v_mul_f32_e32 v61, v190, v190
	v_fmac_f32_e32 v60, v189, v189
	v_fmac_f32_e32 v61, v191, v191
	v_add_f32_e32 v60, v60, v61
	v_add_f32_e32 v97, v97, v60
	s_waitcnt vmcnt(4)
; __device__ __forceinline__ float bf_lo(unsigned w) { return __uint_as_float(w << 16); }
; __device__ __forceinline__ float bf_hi(unsigned w) { return __uint_as_float(w & 0xffff0000u); }
; __device__ __forceinline__ float wave_sum(float v) {
; #pragma unroll
;     for (int o = 1; o < 64; o <<= 1) v += __shfl_xor(v, o);
;     return v;
; }
; __device__ __forceinline__ void final_norm(const Frame& F) {
;     ...
;         for (int rr = 0; rr < NR; ++rr) { f32x4 v[4]; float s = 0.f;
; #pragma unroll
;             for (int j = 0; j < 4; ++j) { v[j] = (f32x4){pg8::bf_lo(w[rr][j].x), pg8::bf_hi(w[rr][j].x), pg8::bf_lo(w[rr][j].y), pg8::bf_hi(w[rr][j].y)}; s += (v[j].x * v[j].x + v[j].y * v[j].y) + (v[j].z * v[j].z + v[j].w * v[j].w); }
;             const float rstd = 1.0f / sqrtf(wave_sum(s) * (1.0f / DM) + EPS);
	v_lshlrev_b32_e32 v192, 16, v136
	v_and_b32_e32 v193, 0xffff0000, v136
	v_lshlrev_b32_e32 v194, 16, v137
	v_and_b32_e32 v195, 0xffff0000, v137
	v_lshlrev_b32_e32 v196, 16, v138
	v_and_b32_e32 v197, 0xffff0000, v138
	v_lshlrev_b32_e32 v198, 16, v139
	v_and_b32_e32 v199, 0xffff0000, v139
	v_lshlrev_b32_e32 v200, 16, v140
	v_and_b32_e32 v201, 0xffff0000, v140
	v_lshlrev_b32_e32 v202, 16, v141
	v_and_b32_e32 v203, 0xffff0000, v141
	v_lshlrev_b32_e32 v204, 16, v142
	v_and_b32_e32 v205, 0xffff0000, v142
	v_lshlrev_b32_e32 v206, 16, v143
	v_and_b32_e32 v207, 0xffff0000, v143
	v_mul_f32_e32 v60, v192, v192
	v_mul_f32_e32 v61, v194, v194
	v_fmac_f32_e32 v60, v193, v193
	v_fmac_f32_e32 v61, v195, v195
	v_add_f32_e32 v98, v60, v61
	v_mul_f32_e32 v60, v196, v196
	v_mul_f32_e32 v61, v198, v198
	v_fmac_f32_e32 v60, v197, v197
	v_fmac_f32_e32 v61, v199, v199
	v_add_f32_e32 v60, v60, v61
	v_add_f32_e32 v98, v98, v60
	v_mul_f32_e32 v60, v200, v200
	v_mul_f32_e32 v61, v202, v202
	v_fmac_f32_e32 v60, v201, v201
	v_fmac_f32_e32 v61, v203, v203
	v_add_f32_e32 v60, v60, v61
	v_add_f32_e32 v98, v98, v60
	v_mul_f32_e32 v60, v204, v204
	v_mul_f32_e32 v61, v206, v206
	v_fmac_f32_e32 v60, v205, v205
	v_fmac_f32_e32 v61, v207, v207
	v_add_f32_e32 v60, v60, v61
	v_add_f32_e32 v98, v98, v60
	s_waitcnt vmcnt(0)
	v_lshlrev_b32_e32 v208, 16, v144
	v_and_b32_e32 v209, 0xffff0000, v144
	v_lshlrev_b32_e32 v210, 16, v145
	v_and_b32_e32 v211, 0xffff0000, v145
	v_lshlrev_b32_e32 v212, 16, v146
	v_and_b32_e32 v213, 0xffff0000, v146
	v_lshlrev_b32_e32 v214, 16, v147
	v_and_b32_e32 v215, 0xffff0000, v147
	v_lshlrev_b32_e32 v216, 16, v148
	v_and_b32_e32 v217, 0xffff0000, v148
	v_lshlrev_b32_e32 v218, 16, v149
	v_and_b32_e32 v219, 0xffff0000, v149
	v_lshlrev_b32_e32 v220, 16, v150
	v_and_b32_e32 v221, 0xffff0000, v150
	v_lshlrev_b32_e32 v222, 16, v151
	v_and_b32_e32 v223, 0xffff0000, v151
	v_mul_f32_e32 v60, v208, v208
	v_mul_f32_e32 v61, v210, v210
	v_fmac_f32_e32 v60, v209, v209
	v_fmac_f32_e32 v61, v211, v211
	v_add_f32_e32 v99, v60, v61
	v_mul_f32_e32 v60, v212, v212
	v_mul_f32_e32 v61, v214, v214
	v_fmac_f32_e32 v60, v213, v213
	v_fmac_f32_e32 v61, v215, v215
	v_add_f32_e32 v60, v60, v61
	v_add_f32_e32 v99, v99, v60
	v_mul_f32_e32 v60, v216, v216
	v_mul_f32_e32 v61, v218, v218
	v_fmac_f32_e32 v60, v217, v217
	v_fmac_f32_e32 v61, v219, v219
	v_add_f32_e32 v60, v60, v61
	v_add_f32_e32 v99, v99, v60
	v_mul_f32_e32 v60, v220, v220
	v_mul_f32_e32 v61, v222, v222
	v_fmac_f32_e32 v60, v221, v221
	v_fmac_f32_e32 v61, v223, v223
	v_add_f32_e32 v60, v60, v61
	v_add_f32_e32 v99, v99, v60
	ds_bpermute_b32 v92, v38, v96
	ds_bpermute_b32 v93, v38, v97
	ds_bpermute_b32 v94, v38, v98
	ds_bpermute_b32 v95, v38, v99
	s_waitcnt lgkmcnt(0)
	v_add_f32_e32 v96, v96, v92
	v_add_f32_e32 v97, v97, v93
	v_add_f32_e32 v98, v98, v94
	v_add_f32_e32 v99, v99, v95
	ds_bpermute_b32 v92, v39, v96
	ds_bpermute_b32 v93, v39, v97
	ds_bpermute_b32 v94, v39, v98
	ds_bpermute_b32 v95, v39, v99
	s_waitcnt lgkmcnt(0)
	v_add_f32_e32 v96, v96, v92
	v_add_f32_e32 v97, v97, v93
	v_add_f32_e32 v98, v98, v94
	v_add_f32_e32 v99, v99, v95
	ds_bpermute_b32 v92, v40, v96
	ds_bpermute_b32 v93, v40, v97
	ds_bpermute_b32 v94, v40, v98
	ds_bpermute_b32 v95, v40, v99
	s_waitcnt lgkmcnt(0)
	v_add_f32_e32 v96, v96, v92
	v_add_f32_e32 v97, v97, v93
	v_add_f32_e32 v98, v98, v94
	v_add_f32_e32 v99, v99, v95
	ds_bpermute_b32 v92, v41, v96
	ds_bpermute_b32 v93, v41, v97
	ds_bpermute_b32 v94, v41, v98
	ds_bpermute_b32 v95, v41, v99
	s_waitcnt lgkmcnt(0)
	v_add_f32_e32 v96, v96, v92
	v_add_f32_e32 v97, v97, v93
	v_add_f32_e32 v98, v98, v94
	v_add_f32_e32 v99, v99, v95
	ds_bpermute_b32 v92, v42, v96
	ds_bpermute_b32 v93, v42, v97
	ds_bpermute_b32 v94, v42, v98
	ds_bpermute_b32 v95, v42, v99
	s_waitcnt lgkmcnt(0)
	v_add_f32_e32 v96, v96, v92
	v_add_f32_e32 v97, v97, v93
	v_add_f32_e32 v98, v98, v94
	v_add_f32_e32 v99, v99, v95
	ds_bpermute_b32 v92, v43, v96
	ds_bpermute_b32 v93, v43, v97
	ds_bpermute_b32 v94, v43, v98
	ds_bpermute_b32 v95, v43, v99
	s_waitcnt lgkmcnt(0)
	v_add_f32_e32 v96, v96, v92
	v_add_f32_e32 v97, v97, v93
	v_add_f32_e32 v98, v98, v94
	v_add_f32_e32 v99, v99, v95
	v_fmamk_f32 v96, v96, 0x3a800000, v44
	v_mul_f32_e32 v60, 0x4f800000, v96
	v_cmp_gt_f32_e32 vcc, s15, v96
	s_nop 1
	v_cndmask_b32_e32 v96, v96, v60, vcc
	v_sqrt_f32_e32 v60, v96
	s_nop 0
	v_add_u32_e32 v61, -1, v60
	v_add_u32_e32 v62, 1, v60
	v_fma_f32 v63, -v61, v60, v96
	v_fma_f32 v64, -v62, v60, v96
	v_cmp_ge_f32_e64 s[18:19], 0, v63
	s_nop 1
	v_cndmask_b32_e64 v60, v60, v61, s[18:19]
	v_cmp_lt_f32_e64 s[18:19], 0, v64
	s_nop 1
	v_cndmask_b32_e64 v60, v60, v62, s[18:19]
	v_mul_f32_e32 v61, 0x37800000, v60
	v_cndmask_b32_e32 v60, v60, v61, vcc
	v_cmp_class_f32_e32 vcc, v96, v45
	s_nop 1
	v_cndmask_b32_e32 v65, v60, v96, vcc
	v_div_scale_f32 v63, s[18:19], v65, v65, 1.0
	v_rcp_f32_e32 v64, v63
	s_nop 0
	v_div_scale_f32 v61, vcc, 1.0, v65, 1.0
	v_fma_f32 v62, -v63, v64, 1.0
	v_fmac_f32_e32 v64, v62, v64
	v_mul_f32_e32 v62, v61, v64
	v_fma_f32 v60, -v63, v62, v61
	v_fmac_f32_e32 v62, v60, v64
	v_fma_f32 v61, -v63, v62, v61
	v_div_fmas_f32 v61, v61, v64, v62
	v_div_fixup_f32 v84, v61, v65, 1.0
	v_fmamk_f32 v97, v97, 0x3a800000, v44
	v_mul_f32_e32 v60, 0x4f800000, v97
	v_cmp_gt_f32_e32 vcc, s15, v97
	s_nop 1
	v_cndmask_b32_e32 v97, v97, v60, vcc
	v_sqrt_f32_e32 v60, v97
	s_nop 0
	v_add_u32_e32 v61, -1, v60
	v_add_u32_e32 v62, 1, v60
	v_fma_f32 v63, -v61, v60, v97
	v_fma_f32 v64, -v62, v60, v97
	v_cmp_ge_f32_e64 s[18:19], 0, v63
	s_nop 1
	v_cndmask_b32_e64 v60, v60, v61, s[18:19]
	v_cmp_lt_f32_e64 s[18:19], 0, v64
	s_nop 1
	v_cndmask_b32_e64 v60, v60, v62, s[18:19]
; __device__ __forceinline__ void final_norm(const Frame& F) {
;     ...
;             const float rstd = 1.0f / sqrtf(wave_sum(s) * (1.0f / DM) + EPS);
;             f32x4* xr = (f32x4*)(F.out + (size_t)Rr[rr] * DM) + F.lane;
;             if (has[rr]) {
; #pragma unroll
;                 for (int j = 0; j < 4; ++j) xr[64 * j] = v[j] * rstd * g4[64 * j]; } }
	v_mul_f32_e32 v61, 0x37800000, v60
	v_cndmask_b32_e32 v60, v60, v61, vcc
	v_cmp_class_f32_e32 vcc, v97, v45
	s_nop 1
	v_cndmask_b32_e32 v65, v60, v97, vcc
	v_div_scale_f32 v63, s[18:19], v65, v65, 1.0
	v_rcp_f32_e32 v64, v63
	s_nop 0
	v_div_scale_f32 v61, vcc, 1.0, v65, 1.0
	v_fma_f32 v62, -v63, v64, 1.0
	v_fmac_f32_e32 v64, v62, v64
	v_mul_f32_e32 v62, v61, v64
	v_fma_f32 v60, -v63, v62, v61
	v_fmac_f32_e32 v62, v60, v64
	v_fma_f32 v61, -v63, v62, v61
	v_div_fmas_f32 v61, v61, v64, v62
	v_div_fixup_f32 v86, v61, v65, 1.0
	v_fmamk_f32 v98, v98, 0x3a800000, v44
	v_mul_f32_e32 v60, 0x4f800000, v98
	v_cmp_gt_f32_e32 vcc, s15, v98
	s_nop 1
	v_cndmask_b32_e32 v98, v98, v60, vcc
	v_sqrt_f32_e32 v60, v98
	s_nop 0
	v_add_u32_e32 v61, -1, v60
	v_add_u32_e32 v62, 1, v60
	v_fma_f32 v63, -v61, v60, v98
	v_fma_f32 v64, -v62, v60, v98
	v_cmp_ge_f32_e64 s[18:19], 0, v63
	s_nop 1
	v_cndmask_b32_e64 v60, v60, v61, s[18:19]
	v_cmp_lt_f32_e64 s[18:19], 0, v64
	s_nop 1
	v_cndmask_b32_e64 v60, v60, v62, s[18:19]
	v_mul_f32_e32 v61, 0x37800000, v60
	v_cndmask_b32_e32 v60, v60, v61, vcc
	v_cmp_class_f32_e32 vcc, v98, v45
	s_nop 1
	v_cndmask_b32_e32 v65, v60, v98, vcc
	v_div_scale_f32 v63, s[18:19], v65, v65, 1.0
	v_rcp_f32_e32 v64, v63
	s_nop 0
	v_div_scale_f32 v61, vcc, 1.0, v65, 1.0
	v_fma_f32 v62, -v63, v64, 1.0
	v_fmac_f32_e32 v64, v62, v64
	v_mul_f32_e32 v62, v61, v64
	v_fma_f32 v60, -v63, v62, v61
	v_fmac_f32_e32 v62, v60, v64
	v_fma_f32 v61, -v63, v62, v61
	v_div_fmas_f32 v61, v61, v64, v62
	v_div_fixup_f32 v88, v61, v65, 1.0
	v_fmamk_f32 v99, v99, 0x3a800000, v44
	v_mul_f32_e32 v60, 0x4f800000, v99
	v_cmp_gt_f32_e32 vcc, s15, v99
	s_nop 1
	v_cndmask_b32_e32 v99, v99, v60, vcc
	v_sqrt_f32_e32 v60, v99
	s_nop 0
	v_add_u32_e32 v61, -1, v60
	v_add_u32_e32 v62, 1, v60
	v_fma_f32 v63, -v61, v60, v99
	v_fma_f32 v64, -v62, v60, v99
	v_cmp_ge_f32_e64 s[18:19], 0, v63
	s_nop 1
	v_cndmask_b32_e64 v60, v60, v61, s[18:19]
	v_cmp_lt_f32_e64 s[18:19], 0, v64
	s_nop 1
	v_cndmask_b32_e64 v60, v60, v62, s[18:19]
	v_mul_f32_e32 v61, 0x37800000, v60
	v_cndmask_b32_e32 v60, v60, v61, vcc
	v_cmp_class_f32_e32 vcc, v99, v45
	s_nop 1
	v_cndmask_b32_e32 v65, v60, v99, vcc
	v_div_scale_f32 v63, s[18:19], v65, v65, 1.0
	v_rcp_f32_e32 v64, v63
	s_nop 0
	v_div_scale_f32 v61, vcc, 1.0, v65, 1.0
	v_fma_f32 v62, -v63, v64, 1.0
	v_fmac_f32_e32 v64, v62, v64
	v_mul_f32_e32 v62, v61, v64
	v_fma_f32 v60, -v63, v62, v61
	v_fmac_f32_e32 v62, v60, v64
	v_fma_f32 v61, -v63, v62, v61
	v_div_fmas_f32 v61, v61, v64, v62
	v_div_fixup_f32 v90, v61, v65, 1.0
	s_lshl_b32 s2, s0, 12
	v_lshl_add_u64 v[78:79], v[4:5], 0, s[2:3]
	v_pk_mul_f32 v[160:161], v[84:85], v[160:161] op_sel_hi:[0,1]
	v_pk_mul_f32 v[162:163], v[84:85], v[162:163] op_sel_hi:[0,1]
	v_pk_mul_f32 v[160:161], v[100:101], v[160:161]
	v_pk_mul_f32 v[162:163], v[102:103], v[162:163]
	global_store_dwordx4 v[78:79], v[160:163], off
	v_pk_mul_f32 v[164:165], v[84:85], v[164:165] op_sel_hi:[0,1]
	v_pk_mul_f32 v[166:167], v[84:85], v[166:167] op_sel_hi:[0,1]
	v_pk_mul_f32 v[164:165], v[104:105], v[164:165]
	v_pk_mul_f32 v[166:167], v[106:107], v[166:167]
	global_store_dwordx4 v[78:79], v[164:167], off offset:1024
	v_pk_mul_f32 v[168:169], v[84:85], v[168:169] op_sel_hi:[0,1]
	v_pk_mul_f32 v[170:171], v[84:85], v[170:171] op_sel_hi:[0,1]
	v_pk_mul_f32 v[168:169], v[108:109], v[168:169]
	v_pk_mul_f32 v[170:171], v[110:111], v[170:171]
	global_store_dwordx4 v[78:79], v[168:171], off offset:2048
	v_pk_mul_f32 v[172:173], v[84:85], v[172:173] op_sel_hi:[0,1]
	v_pk_mul_f32 v[174:175], v[84:85], v[174:175] op_sel_hi:[0,1]
	v_pk_mul_f32 v[172:173], v[112:113], v[172:173]
	v_pk_mul_f32 v[174:175], v[114:115], v[174:175]
	global_store_dwordx4 v[78:79], v[172:175], off offset:3072
	s_cmp_lt_i32 s4, 0x8000
	s_cbranch_scc0 .Lfn_skip1
	s_lshl_b32 s2, s4, 12
	v_lshl_add_u64 v[78:79], v[4:5], 0, s[2:3]
	v_pk_mul_f32 v[176:177], v[86:87], v[176:177] op_sel_hi:[0,1]
	v_pk_mul_f32 v[178:179], v[86:87], v[178:179] op_sel_hi:[0,1]
	v_pk_mul_f32 v[176:177], v[100:101], v[176:177]
	v_pk_mul_f32 v[178:179], v[102:103], v[178:179]
	global_store_dwordx4 v[78:79], v[176:179], off
	v_pk_mul_f32 v[180:181], v[86:87], v[180:181] op_sel_hi:[0,1]
	v_pk_mul_f32 v[182:183], v[86:87], v[182:183] op_sel_hi:[0,1]
	v_pk_mul_f32 v[180:181], v[104:105], v[180:181]
	v_pk_mul_f32 v[182:183], v[106:107], v[182:183]
	global_store_dwordx4 v[78:79], v[180:183], off offset:1024
	v_pk_mul_f32 v[184:185], v[86:87], v[184:185] op_sel_hi:[0,1]
	v_pk_mul_f32 v[186:187], v[86:87], v[186:187] op_sel_hi:[0,1]
	v_pk_mul_f32 v[184:185], v[108:109], v[184:185]
	v_pk_mul_f32 v[186:187], v[110:111], v[186:187]
	global_store_dwordx4 v[78:79], v[184:187], off offset:2048
	v_pk_mul_f32 v[188:189], v[86:87], v[188:189] op_sel_hi:[0,1]
	v_pk_mul_f32 v[190:191], v[86:87], v[190:191] op_sel_hi:[0,1]
	v_pk_mul_f32 v[188:189], v[112:113], v[188:189]
	v_pk_mul_f32 v[190:191], v[114:115], v[190:191]
	global_store_dwordx4 v[78:79], v[188:191], off offset:3072
; __device__ __forceinline__ void final_norm(const Frame& F) {
;     ...
;             const float rstd = 1.0f / sqrtf(wave_sum(s) * (1.0f / DM) + EPS);
;             f32x4* xr = (f32x4*)(F.out + (size_t)Rr[rr] * DM) + F.lane;
;             if (has[rr]) {
; #pragma unroll
;                 for (int j = 0; j < 4; ++j) xr[64 * j] = v[j] * rstd * g4[64 * j]; } }
;     }
.Lfn_skip1:
	s_cmp_lt_i32 s5, 0x8000
	s_cbranch_scc0 .Lfn_skip2
	s_lshl_b32 s2, s5, 12
	v_lshl_add_u64 v[78:79], v[4:5], 0, s[2:3]
	v_pk_mul_f32 v[192:193], v[88:89], v[192:193] op_sel_hi:[0,1]
	v_pk_mul_f32 v[194:195], v[88:89], v[194:195] op_sel_hi:[0,1]
	v_pk_mul_f32 v[192:193], v[100:101], v[192:193]
	v_pk_mul_f32 v[194:195], v[102:103], v[194:195]
	global_store_dwordx4 v[78:79], v[192:195], off
	v_pk_mul_f32 v[196:197], v[88:89], v[196:197] op_sel_hi:[0,1]
	v_pk_mul_f32 v[198:199], v[88:89], v[198:199] op_sel_hi:[0,1]
	v_pk_mul_f32 v[196:197], v[104:105], v[196:197]
	v_pk_mul_f32 v[198:199], v[106:107], v[198:199]
	global_store_dwordx4 v[78:79], v[196:199], off offset:1024
	v_pk_mul_f32 v[200:201], v[88:89], v[200:201] op_sel_hi:[0,1]
	v_pk_mul_f32 v[202:203], v[88:89], v[202:203] op_sel_hi:[0,1]
	v_pk_mul_f32 v[200:201], v[108:109], v[200:201]
	v_pk_mul_f32 v[202:203], v[110:111], v[202:203]
	global_store_dwordx4 v[78:79], v[200:203], off offset:2048
	v_pk_mul_f32 v[204:205], v[88:89], v[204:205] op_sel_hi:[0,1]
	v_pk_mul_f32 v[206:207], v[88:89], v[206:207] op_sel_hi:[0,1]
	v_pk_mul_f32 v[204:205], v[112:113], v[204:205]
	v_pk_mul_f32 v[206:207], v[114:115], v[206:207]
	global_store_dwordx4 v[78:79], v[204:207], off offset:3072
.Lfn_skip2:
	s_cmp_lt_i32 s6, 0x8000
	s_cbranch_scc0 .Lfn_skip3
	s_lshl_b32 s2, s6, 12
	v_lshl_add_u64 v[78:79], v[4:5], 0, s[2:3]
	v_pk_mul_f32 v[208:209], v[90:91], v[208:209] op_sel_hi:[0,1]
	v_pk_mul_f32 v[210:211], v[90:91], v[210:211] op_sel_hi:[0,1]
	v_pk_mul_f32 v[208:209], v[100:101], v[208:209]
	v_pk_mul_f32 v[210:211], v[102:103], v[210:211]
	global_store_dwordx4 v[78:79], v[208:211], off
	v_pk_mul_f32 v[212:213], v[90:91], v[212:213] op_sel_hi:[0,1]
	v_pk_mul_f32 v[214:215], v[90:91], v[214:215] op_sel_hi:[0,1]
	v_pk_mul_f32 v[212:213], v[104:105], v[212:213]
	v_pk_mul_f32 v[214:215], v[106:107], v[214:215]
	global_store_dwordx4 v[78:79], v[212:215], off offset:1024
	v_pk_mul_f32 v[216:217], v[90:91], v[216:217] op_sel_hi:[0,1]
	v_pk_mul_f32 v[218:219], v[90:91], v[218:219] op_sel_hi:[0,1]
	v_pk_mul_f32 v[216:217], v[108:109], v[216:217]
	v_pk_mul_f32 v[218:219], v[110:111], v[218:219]
	global_store_dwordx4 v[78:79], v[216:219], off offset:2048
	v_pk_mul_f32 v[220:221], v[90:91], v[220:221] op_sel_hi:[0,1]
	v_pk_mul_f32 v[222:223], v[90:91], v[222:223] op_sel_hi:[0,1]
	v_pk_mul_f32 v[220:221], v[112:113], v[220:221]
	v_pk_mul_f32 v[222:223], v[114:115], v[222:223]
	global_store_dwordx4 v[78:79], v[220:223], off offset:3072
.Lfn_skip3:
	s_lshl_b32 s1, s12, 2
	s_add_i32 s0, s0, s1
	s_cmp_lt_i32 s0, 0x8000
	s_cbranch_scc1 .LBB0_802
